# hazard fix: last P conversion of a query block now two MFMAs ahead of its first PV MFMA (VALU-write -> MFMA-read distance); otherwise as previous
# baseline (speedup 1.0000x reference)
; __device__ __forceinline__ unsigned pk2(float lo, float hi) { f32x2_t v = {lo, hi}; bf16x2_t b = __builtin_convertvector(v, bf16x2_t); return __builtin_bit_cast(unsigned, b); }
; template <int DQK, bool MASK, int NQ>
; __device__ __forceinline__ void attn_unit(unsigned char* lds, const bf16_t* Qg, int ldq, const bf16_t* Kg, int ldk, const bf16_t* Vtg, bf16_t* Og, int ldo,
;                                           int qi0, int a0, int n1, int b0, int n2, float m0, bool sink) {
;     ...
;             bf16x8 pf[NQ];
; #pragma unroll
;             for (int qb = 0; qb < NQ; ++qb) {
; #pragma unroll
;                 for (int k2 = 0; k2 < 2; ++k2)
; #pragma unroll
;                     for (int j = 0; j < 4; ++j) sc[k2][qb][j] = __builtin_amdgcn_exp2f(sc[k2][qb][j]);
;                 u32x4 w; w.x = pk2(sc[0][qb][0], sc[0][qb][1]); w.y = pk2(sc[0][qb][2], sc[0][qb][3]); w.z = pk2(sc[1][qb][0], sc[1][qb][1]); w.w = pk2(sc[1][qb][2], sc[1][qb][3]);
;                 pf[qb] = __builtin_bit_cast(bf16x8, w); }
;             { const unsigned char* vb_ = lds + VOFF + (tt & 1) * VBYTES + (hb * 4 + g) * 16;
; #pragma unroll
;               for (int eb = 0; eb < 4; ++eb) {
;                   const bf16x8 vf = *(const bf16x8*)(vb_ + (eb * 16 + ql) * (VP * 2));
; #pragma unroll
;                   for (int qb = 0; qb < NQ; ++qb) o[eb][qb] = __builtin_amdgcn_mfma_f32_16x16x32_bf16(vf, pf[qb], o[eb][qb], 0, 0, 0);
;               }
; #pragma unroll
;               for (int qb = 0; qb < NQ; ++qb) ol[qb] = __builtin_amdgcn_mfma_f32_16x16x32_bf16(ones, pf[qb], ol[qb], 0, 0, 0); }
;           }
;         }
;         if (tt + 1 < nt) ATT_COMMIT((tt + 1) & 1);
.Lmla_common_b:
	v_exp_f32_e32 v216, v216
	v_exp_f32_e32 v217, v217
	v_exp_f32_e32 v218, v218
	v_exp_f32_e32 v219, v219
	v_exp_f32_e32 v232, v232
	v_exp_f32_e32 v233, v233
	v_exp_f32_e32 v234, v234
	v_exp_f32_e32 v235, v235
	v_cvt_pk_bf16_f32 v216, v216, v217
	v_cvt_pk_bf16_f32 v217, v218, v219
	v_cvt_pk_bf16_f32 v218, v232, v233
	v_cvt_pk_bf16_f32 v219, v234, v235
	s_nop 1
	s_waitcnt lgkmcnt(3)
	v_mfma_f32_16x16x32_bf16 v[76:79], v[196:199], v[216:219], v[76:79]
	v_exp_f32_e32 v220, v220
	v_exp_f32_e32 v221, v221
	v_exp_f32_e32 v222, v222
	v_exp_f32_e32 v223, v223
	s_waitcnt lgkmcnt(2)
	v_mfma_f32_16x16x32_bf16 v[80:83], v[192:195], v[216:219], v[80:83]
	v_exp_f32_e32 v44, v44
	v_exp_f32_e32 v45, v45
	v_exp_f32_e32 v46, v46
	v_exp_f32_e32 v47, v47
	s_waitcnt lgkmcnt(1)
	v_mfma_f32_16x16x32_bf16 v[84:87], v[188:191], v[216:219], v[84:87]
	v_cvt_pk_bf16_f32 v220, v220, v221
	v_cvt_pk_bf16_f32 v221, v222, v223
	v_cvt_pk_bf16_f32 v222, v44, v45
	v_cvt_pk_bf16_f32 v223, v46, v47
	s_waitcnt lgkmcnt(0)
	v_mfma_f32_16x16x32_bf16 v[72:75], v[184:187], v[216:219], v[72:75]
	v_mfma_f32_16x16x32_bf16 v[88:91], v[246:249], v[216:219], v[88:91]
	v_mfma_f32_16x16x32_bf16 v[56:59], v[196:199], v[220:223], v[56:59]
	v_exp_f32_e32 v224, v224
	v_exp_f32_e32 v225, v225
	v_exp_f32_e32 v226, v226
	v_exp_f32_e32 v227, v227
	v_mfma_f32_16x16x32_bf16 v[60:63], v[192:195], v[220:223], v[60:63]
	v_exp_f32_e32 v200, v200
	v_exp_f32_e32 v201, v201
	v_exp_f32_e32 v202, v202
	v_exp_f32_e32 v203, v203
	v_mfma_f32_16x16x32_bf16 v[64:67], v[188:191], v[220:223], v[64:67]
	v_cvt_pk_bf16_f32 v224, v224, v225
	v_cvt_pk_bf16_f32 v225, v226, v227
	v_cvt_pk_bf16_f32 v226, v200, v201
	v_cvt_pk_bf16_f32 v227, v202, v203
	v_mfma_f32_16x16x32_bf16 v[52:55], v[184:187], v[220:223], v[52:55]
	v_mfma_f32_16x16x32_bf16 v[68:71], v[246:249], v[220:223], v[68:71]
	v_mfma_f32_16x16x32_bf16 v[24:27], v[196:199], v[224:227], v[24:27]
	v_exp_f32_e32 v228, v228
	v_exp_f32_e32 v229, v229
	v_exp_f32_e32 v230, v230
	v_exp_f32_e32 v231, v231
	v_mfma_f32_16x16x32_bf16 v[28:31], v[192:195], v[224:227], v[28:31]
	v_exp_f32_e32 v236, v236
	v_exp_f32_e32 v237, v237
	v_exp_f32_e32 v238, v238
	v_exp_f32_e32 v239, v239
	v_mfma_f32_16x16x32_bf16 v[32:35], v[188:191], v[224:227], v[32:35]
	v_cvt_pk_bf16_f32 v228, v228, v229
	v_cvt_pk_bf16_f32 v229, v230, v231
	v_cvt_pk_bf16_f32 v230, v236, v237
	v_cvt_pk_bf16_f32 v231, v238, v239
	v_mfma_f32_16x16x32_bf16 v[20:23], v[184:187], v[224:227], v[20:23]
	v_mfma_f32_16x16x32_bf16 v[48:51], v[246:249], v[224:227], v[48:51]
	v_mfma_f32_16x16x32_bf16 v[4:7], v[196:199], v[228:231], v[4:7]
	v_mfma_f32_16x16x32_bf16 v[8:11], v[192:195], v[228:231], v[8:11]
	v_mfma_f32_16x16x32_bf16 v[12:15], v[188:191], v[228:231], v[12:15]
	v_mfma_f32_16x16x32_bf16 v[0:3], v[184:187], v[228:231], v[0:3]
	v_mfma_f32_16x16x32_bf16 v[16:19], v[246:249], v[228:231], v[16:19]
	s_cmp_ge_i32 s24, s19
	s_cbranch_scc1 .Lmla_nocommit
	s_and_b32 s0, s24, 1
	s_mul_i32 s1, s0, 0x3000
	v_add_u32_e32 v37, s1, v205
	s_waitcnt vmcnt(1)
	ds_write_b128 v37, v[140:143]
	s_and_saveexec_b64 s[14:15], s[38:39]
	ds_write_b128 v37, v[144:147] offset:8192
	s_or_b64 exec, exec, s[14:15]
	s_mulk_i32 s0, 0x2400
	v_add_u32_e32 v37, s0, v209
	v_add_u32_e32 v37, 0x6000, v37
	s_waitcnt vmcnt(0)
	ds_write2_b64 v37, v[148:149], v[150:151] offset1:2
